# staging waves: a short sleep after every shared-buffer LDS write and partial read, and inside the private prefix pass
# speedup vs baseline: 1.0190x; 1.0014x over previous
.Lsc_G:
	v_add_u32_e32 v1, 0xffffff00, v173
	v_lshrrev_b32_e32 v2, 3, v1
	v_and_b32_e32 v3, 7, v1
	s_and_b32 s8, s4, 7
	s_bfe_u32 s10, s4, 0x20003
	s_lshr_b32 s11, s4, 7
	s_bfe_u32 s9, s4, 0x20005
	s_lshl_b32 s9, s9, 13
	v_readlane_b32 s50, v242, 0
	v_readlane_b32 s51, v242, 1
	v_readlane_b32 s16, v242, 62
	s_load_dwordx4 s[12:15], s[50:51], 0x68
	s_add_u32 s36, s90, 0x5e00000
	s_addc_u32 s37, s91, 0
	s_add_u32 s38, s90, 0x7e00000
	s_addc_u32 s39, s91, 0
	s_add_u32 s44, s90, 0x9e00000
	s_addc_u32 s45, s91, 0
	s_add_u32 s46, s90, 0x1c00000
	s_addc_u32 s47, s91, 0
	s_lshl_b32 s68, s11, 25
	s_add_u32 s69, s68, 0x13e00000
	s_add_u32 s40, s90, s69
	s_addc_u32 s41, s91, 0
	s_add_u32 s69, s68, 0x17e00000
	s_add_u32 s42, s90, s69
	s_addc_u32 s43, s91, 0
	s_lshl_b32 s68, s11, 26
	s_add_u32 s68, s68, 0xbe00000
	s_add_u32 s48, s90, s68
	s_addc_u32 s49, s91, 0
	s_cmp_eq_u32 s11, 0
	s_mov_b32 s54, 0x8000
	s_movk_i32 s55, 0x400
	s_mov_b32 s64, 0x10000
	s_cselect_b32 s54, s54, 0xffff8000
	s_cselect_b32 s55, s55, 0xfffffc00
	s_cselect_b32 s64, s64, 0xffff0000
	s_cselect_b64 vcc, -1, 0
	v_sub_u32_e32 v4, 0x1fff, v2
	s_nop 3
	v_cndmask_b32_e32 v4, v4, v2, vcc
	v_add_u32_e32 v4, s9, v4
	s_lshl_b32 s68, s8, 7
	v_lshlrev_b32_e32 v5, 10, v4
	v_lshl_add_u32 v5, v3, 3, v5
	v_add_u32_e32 v5, s68, v5
	s_lshl_b32 s69, s8, 2
	v_lshlrev_b32_e32 v6, 5, v4
	v_add_u32_e32 v6, s69, v6
	s_lshl_b32 s69, s10, 5
	s_add_i32 s69, s69, s68
	v_lshlrev_b32_e32 v9, 10, v4
	v_lshl_add_u32 v9, v3, 2, v9
	v_add_u32_e32 v9, s69, v9
	s_lshl_b32 s65, s69, 1
	v_mul_u32_u24_e32 v8, 1024, v2
	v_lshl_add_u32 v8, v3, 4, v8
	v_add_u32_e32 v138, 512, v8
	v_add_u32_e32 v140, 35328, v8
	v_add_u32_e32 v152, -4, v0
	v_mul_u32_u24_e32 v152, 4608, v152
	v_add_u32_e32 v152, 143936, v152
	v_and_b32_e32 v156, 7, v2
	v_lshlrev_b32_e32 v153, 8, v156
	v_lshl_add_u32 v153, v3, 4, v153
	v_add_u32_e32 v153, v152, v153
	v_and_b32_e32 v154, 63, v1
	v_lshl_add_u32 v154, v154, 2, v152
	v_add_u32_e32 v155, 2048, v154
	v_add_u32_e32 v139, -1, v2
	v_mul_u32_u24_e32 v139, 1024, v139
	v_lshl_add_u32 v139, v3, 4, v139
	v_add_u32_e32 v141, 35328, v139
	v_add_u32_e32 v139, 512, v139
	v_cmp_eq_u32_e32 vcc, 0, v2
	s_nop 1
	v_cndmask_b32_e32 v139, v139, v152, vcc
	v_cndmask_b32_e32 v141, v141, v152, vcc
	v_lshrrev_b32_e32 v158, 3, v2
	v_lshlrev_b32_e32 v158, 8, v158
	v_lshl_add_u32 v158, v3, 4, v158
	v_and_b32_e32 v159, 63, v1
	v_lshlrev_b32_e32 v159, 2, v159
	v_add_u32_e32 v106, -4, v0
	v_lshl_add_u32 v159, v106, 8, v159
	v_add_u32_e32 v159, 33792, v159
	v_add_u32_e32 v106, -4, v0
	v_lshlrev_b32_e32 v162, 2, v106
	v_add_u32_e32 v162, 139808, v162
	v_mov_b32_e32 v163, 139808
	v_and_b32_e32 v181, 63, v1
	v_lshlrev_b32_e32 v181, 2, v181
	v_add_u32_e32 v181, 139840, v181
	v_lshl_add_u32 v180, v106, 8, v181
	v_cmp_gt_u32_e32 vcc, v106, v169
	s_nop 1
	v_cndmask_b32_e64 v174, 0, -1, vcc
	v_mov_b32_e32 v177, 0x7fffffff
	v_cndmask_b32_e32 v177, v177, v169, vcc
	v_cmp_lt_u32_e32 vcc, 1, v106
	s_nop 1
	v_cndmask_b32_e64 v175, 0, -1, vcc
	v_mov_b32_e32 v178, 0x7fffffff
	v_cndmask_b32_e32 v178, v178, v169, vcc
	v_cmp_lt_u32_e32 vcc, 2, v106
	s_nop 1
	v_cndmask_b32_e64 v176, 0, -1, vcc
	v_mov_b32_e32 v179, 0x7fffffff
	v_cndmask_b32_e32 v179, v179, v169, vcc
	v_add_u32_e32 v158, 32768, v158
	v_mul_u32_u24_e32 v142, 288, v3
	v_lshl_add_u32 v142, v2, 2, v142
	v_add_u32_e32 v143, 71936, v142
	v_add_u32_e32 v142, 69632, v142
	s_lshl_b32 s69, s8, 6
	s_add_i32 s69, s69, s16
	v_lshl_add_u32 v106, v3, 2, s69
	v_lshlrev_b32_e32 v106, 2, v106
	s_waitcnt lgkmcnt(0)
	global_load_dwordx4 v[12:15], v106, s[12:13]
	global_load_dwordx4 v[16:19], v106, s[12:13] offset:128
	global_load_dwordx4 v[20:23], v106, s[14:15]
	global_load_dwordx4 v[24:27], v106, s[14:15] offset:128
	global_load_dwordx2 v[28:29], v5, s[36:37]
	global_load_dwordx2 v[30:31], v5, s[36:37] offset:64
	global_load_dwordx2 v[32:33], v5, s[38:39]
	global_load_dwordx2 v[34:35], v5, s[38:39] offset:64
	global_load_dwordx2 v[36:37], v5, s[40:41]
	global_load_dwordx2 v[38:39], v5, s[40:41] offset:64
	global_load_dwordx2 v[40:41], v5, s[42:43]
	global_load_dwordx2 v[42:43], v5, s[42:43] offset:64
	global_load_dword v44, v6, s[46:47]
	global_load_dword v45, v9, s[44:45]
	v_add_u32_e32 v5, s54, v5
	v_add_u32_e32 v6, s55, v6
	v_add_u32_e32 v9, s54, v9
	global_load_dwordx2 v[46:47], v5, s[36:37]
	global_load_dwordx2 v[48:49], v5, s[36:37] offset:64
	global_load_dwordx2 v[50:51], v5, s[38:39]
	global_load_dwordx2 v[52:53], v5, s[38:39] offset:64
	global_load_dwordx2 v[54:55], v5, s[40:41]
	global_load_dwordx2 v[56:57], v5, s[40:41] offset:64
	global_load_dwordx2 v[58:59], v5, s[42:43]
	global_load_dwordx2 v[60:61], v5, s[42:43] offset:64
	global_load_dword v62, v6, s[46:47]
	global_load_dword v63, v9, s[44:45]
	v_add_u32_e32 v5, s54, v5
	v_add_u32_e32 v6, s55, v6
	v_add_u32_e32 v9, s54, v9
	v_and_b32_e32 v166, 15, v1
	v_lshrrev_b32_e32 v167, 4, v1
	v_sub_u32_e32 v4, 0x1fff, v167
	s_cmp_eq_u32 s11, 0
	s_cselect_b64 vcc, -1, 0
	s_nop 3
	v_cndmask_b32_e32 v4, v4, v167, vcc
	v_add_u32_e32 v4, s9, v4
	v_lshlrev_b32_e32 v7, 11, v4
	v_lshl_add_u32 v7, v166, 2, v7
	v_add_u32_e32 v7, s65, v7
	s_ashr_i32 s65, s64, 1
	v_add_u32_e32 v165, s65, v7
	v_lshlrev_b32_e32 v11, 10, v167
	v_lshl_add_u32 v11, v166, 6, v11
	v_add_u32_e32 v11, 74240, v11
	v_lshrrev_b32_e32 v166, 2, v166
	v_add_u32_e32 v2, 0, v166
	v_and_b32_e32 v2, 3, v2
	v_lshl_add_u32 v2, v2, 4, v11
	v_add_u32_e32 v3, 1, v166
	v_and_b32_e32 v3, 3, v3
	v_lshl_add_u32 v3, v3, 4, v11
	v_add_u32_e32 v4, 2, v166
	v_and_b32_e32 v4, 3, v4
	v_lshl_add_u32 v4, v4, 4, v11
	v_add_u32_e32 v10, 3, v166
	v_and_b32_e32 v10, 3, v10
	v_lshl_add_u32 v10, v10, 4, v11
	s_waitcnt vmcnt(20)
	v_pk_add_f32 v[190:191], v[20:21], 1.0 op_sel_hi:[1,0] neg_lo:[1,0] neg_hi:[1,0]
	v_pk_add_f32 v[192:193], v[22:23], 1.0 op_sel_hi:[1,0] neg_lo:[1,0] neg_hi:[1,0]
	v_pk_add_f32 v[194:195], v[24:25], 1.0 op_sel_hi:[1,0] neg_lo:[1,0] neg_hi:[1,0]
	v_pk_add_f32 v[196:197], v[26:27], 1.0 op_sel_hi:[1,0] neg_lo:[1,0] neg_hi:[1,0]
	v_cmp_eq_u32_e64 s[12:13], 0, v156
	s_mov_b32 s14, 0x3fb8aa3b
	s_mov_b32 s6, 0
	v_mov_b32_e32 v144, 139792
	v_mov_b32_e32 v145, v164
	v_mov_b32_e32 v146, 0
	s_waitcnt vmcnt(10)
	v_lshlrev_b32_e32 v64, 16, v36
	v_and_b32_e32 v65, 0xffff0000, v36
	v_lshlrev_b32_e32 v66, 16, v37
	v_and_b32_e32 v67, 0xffff0000, v37
	v_lshlrev_b32_e32 v68, 16, v38
	v_and_b32_e32 v69, 0xffff0000, v38
	v_lshlrev_b32_e32 v70, 16, v39
	v_and_b32_e32 v71, 0xffff0000, v39
	ds_write_b128 v153, v[64:67]
	s_sleep 1
	ds_write_b128 v153, v[68:71] offset:128
	s_waitcnt lgkmcnt(0)
	ds_read_b32 v124, v154 offset:0
	ds_read_b32 v125, v154 offset:256
	ds_read_b32 v126, v154 offset:512
	ds_read_b32 v127, v154 offset:768
	ds_read_b32 v128, v154 offset:1024
	ds_read_b32 v129, v154 offset:1280
	ds_read_b32 v130, v154 offset:1536
	ds_read_b32 v131, v154 offset:1792
	v_lshlrev_b32_e32 v108, 16, v32
	v_and_b32_e32 v109, 0xffff0000, v32
	v_lshlrev_b32_e32 v110, 16, v40
	v_and_b32_e32 v111, 0xffff0000, v40
	v_lshlrev_b32_e32 v96, 16, v28
	v_and_b32_e32 v97, 0xffff0000, v28
	v_pk_mul_f32 v[114:115], v[12:13], v[108:109]
	v_pk_fma_f32 v[112:113], v[20:21], v[110:111], v[190:191]
	v_pk_mul_f32 v[88:89], v[44:45], v[114:115] op_sel_hi:[0,1]
	v_pk_mul_f32 v[72:73], v[112:113], v[108:109]
	v_pk_mul_f32 v[80:81], v[88:89], v[110:111]
	v_lshlrev_b32_e32 v108, 16, v33
	v_and_b32_e32 v109, 0xffff0000, v33
	v_lshlrev_b32_e32 v110, 16, v41
	v_and_b32_e32 v111, 0xffff0000, v41
	v_lshlrev_b32_e32 v98, 16, v29
	v_and_b32_e32 v99, 0xffff0000, v29
	v_pk_mul_f32 v[114:115], v[14:15], v[108:109]
	v_pk_fma_f32 v[112:113], v[22:23], v[110:111], v[192:193]
	v_pk_mul_f32 v[90:91], v[44:45], v[114:115] op_sel_hi:[0,1]
	v_pk_mul_f32 v[74:75], v[112:113], v[108:109]
	v_pk_mul_f32 v[82:83], v[90:91], v[110:111]
	v_lshlrev_b32_e32 v108, 16, v34
	v_and_b32_e32 v109, 0xffff0000, v34
	v_lshlrev_b32_e32 v110, 16, v42
	v_and_b32_e32 v111, 0xffff0000, v42
	v_lshlrev_b32_e32 v100, 16, v30
	v_and_b32_e32 v101, 0xffff0000, v30
	v_pk_mul_f32 v[114:115], v[16:17], v[108:109]
	v_pk_fma_f32 v[112:113], v[24:25], v[110:111], v[194:195]
	v_pk_mul_f32 v[92:93], v[44:45], v[114:115] op_sel_hi:[0,1]
	v_pk_mul_f32 v[76:77], v[112:113], v[108:109]
	v_pk_mul_f32 v[84:85], v[92:93], v[110:111]
	v_lshlrev_b32_e32 v108, 16, v35
	v_and_b32_e32 v109, 0xffff0000, v35
	v_lshlrev_b32_e32 v110, 16, v43
	v_and_b32_e32 v111, 0xffff0000, v43
	v_lshlrev_b32_e32 v102, 16, v31
	v_and_b32_e32 v103, 0xffff0000, v31
	v_pk_mul_f32 v[114:115], v[18:19], v[108:109]
	v_pk_fma_f32 v[112:113], v[26:27], v[110:111], v[196:197]
	v_pk_mul_f32 v[94:95], v[44:45], v[114:115] op_sel_hi:[0,1]
	v_pk_mul_f32 v[78:79], v[112:113], v[108:109]
	v_pk_mul_f32 v[86:87], v[94:95], v[110:111]
	v_lshlrev_b32_e32 v104, 16, v45
	v_and_b32_e32 v105, 0xffff0000, v45
	s_waitcnt lgkmcnt(0)
	v_add_f32_e32 v125, v124, v125
	v_add_f32_e32 v126, v125, v126
	v_add_f32_e32 v127, v126, v127
	v_add_f32_e32 v128, v127, v128
	v_add_f32_e32 v129, v128, v129
	v_add_f32_e32 v130, v129, v130
	v_add_f32_e32 v131, v130, v131
	s_and_b32 s72, s6, 3
	s_lshl_b32 s72, s72, 10
	v_add_u32_e32 v182, s72, v180
	v_add_u32_e32 v183, s72, v181
	v_mul_f32_e32 v189, 0x3fb8aa3b, v131
	ds_write_b32 v182, v189
	v_add_u32_e32 v184, 1, v146
	s_waitcnt lgkmcnt(0)
	ds_write_b32 v162, v184
	s_add_u32 s73, s6, 1
	s_mov_b32 s69, 0x100000

.Lsc_gf_go1:
	ds_read_b32 v185, v183
	ds_read_b32 v186, v183 offset:256
	ds_read_b32 v187, v183 offset:512
	s_waitcnt lgkmcnt(0)
	v_and_b32_e32 v185, v174, v185
	v_and_b32_e32 v186, v175, v186
	v_and_b32_e32 v187, v176, v187
	v_add_f32_e32 v185, v185, v186
	v_add_f32_e32 v185, v185, v187
	v_fma_f32 v124, v124, s14, v185
	v_fma_f32 v125, v125, s14, v185
	v_fma_f32 v126, v126, s14, v185
	v_fma_f32 v127, v127, s14, v185
	v_fma_f32 v128, v128, s14, v185
	v_fma_f32 v129, v129, s14, v185
	v_fma_f32 v130, v130, s14, v185
	v_fma_f32 v131, v131, s14, v185
	v_exp_f32_e64 v188, -v185
	v_exp_f32_e64 v124, -v124
	v_exp_f32_e64 v125, -v125
	v_exp_f32_e64 v126, -v126
	v_exp_f32_e64 v127, -v127
	v_exp_f32_e64 v128, -v128
	v_exp_f32_e64 v129, -v129
	v_exp_f32_e64 v130, -v130
	v_exp_f32_e64 v131, -v131
	s_nop 0
	ds_write_b32 v155, v188
	ds_write_b32 v155, v124 offset:256
	ds_write_b32 v155, v125 offset:512
	ds_write_b32 v155, v126 offset:768
	s_sleep 1
	ds_write_b32 v155, v127 offset:1024
	ds_write_b32 v155, v128 offset:1280
	ds_write_b32 v155, v129 offset:1536
	s_sleep 1
	ds_write_b32 v155, v130 offset:1792
	ds_write_b32 v155, v131 offset:2048
	v_mov_b32_e32 v161, v131
	s_waitcnt lgkmcnt(0)
	ds_read_b128 v[64:67], v153 offset:2048
	ds_read_b128 v[68:71], v153 offset:2176
	ds_read_b128 v[116:119], v153 offset:2304
	ds_read_b128 v[120:123], v153 offset:2432
	s_waitcnt lgkmcnt(0)
	v_rcp_f32_e32 v124, v116
	v_rcp_f32_e32 v125, v117
	v_rcp_f32_e32 v126, v118
	v_rcp_f32_e32 v127, v119
	v_rcp_f32_e32 v128, v120
	v_rcp_f32_e32 v129, v121
	v_rcp_f32_e32 v130, v122
	v_rcp_f32_e32 v131, v123
	s_nop 1
	v_pk_mul_f32 v[72:73], v[72:73], v[124:125]
	v_pk_mul_f32 v[80:81], v[80:81], v[124:125]
	v_pk_mul_f32 v[88:89], v[88:89], v[64:65]
	v_pk_mul_f32 v[96:97], v[96:97], v[116:117]
	v_pk_mul_f32 v[74:75], v[74:75], v[126:127]
	v_pk_mul_f32 v[82:83], v[82:83], v[126:127]
	v_pk_mul_f32 v[90:91], v[90:91], v[66:67]
	v_pk_mul_f32 v[98:99], v[98:99], v[118:119]
	v_pk_mul_f32 v[76:77], v[76:77], v[128:129]
	v_pk_mul_f32 v[84:85], v[84:85], v[128:129]
	v_pk_mul_f32 v[92:93], v[92:93], v[68:69]
	v_pk_mul_f32 v[100:101], v[100:101], v[120:121]
	v_pk_mul_f32 v[78:79], v[78:79], v[130:131]
	v_pk_mul_f32 v[86:87], v[86:87], v[130:131]
	v_pk_mul_f32 v[94:95], v[94:95], v[70:71]
	v_pk_mul_f32 v[102:103], v[102:103], v[122:123]
	global_load_dwordx2 v[28:29], v5, s[36:37]
	global_load_dwordx2 v[30:31], v5, s[36:37] offset:64
	global_load_dwordx2 v[32:33], v5, s[38:39]
	global_load_dwordx2 v[34:35], v5, s[38:39] offset:64
	global_load_dwordx2 v[36:37], v5, s[40:41]
	global_load_dwordx2 v[38:39], v5, s[40:41] offset:64
	global_load_dwordx2 v[40:41], v5, s[42:43]
	global_load_dwordx2 v[42:43], v5, s[42:43] offset:64
	global_load_dword v44, v6, s[46:47]
	global_load_dword v45, v9, s[44:45]
	v_add_u32_e32 v5, s54, v5
	v_add_u32_e32 v6, s55, v6
	v_add_u32_e32 v9, s54, v9
	ds_write_b32 v159, v161 offset:0
	s_sleep 1
	ds_write_b128 v8, v[72:75] offset:0
	s_sleep 1
	ds_write_b128 v8, v[76:79] offset:128
	s_sleep 1
	ds_write_b128 v8, v[80:83] offset:256
	s_sleep 1
	ds_write_b128 v8, v[84:87] offset:384
	s_sleep 1
	ds_write2_b32 v138, v96, v97 offset0:1 offset1:3
	s_sleep 1
	ds_write2_b32 v139, v88, v89 offset0:0 offset1:2
	s_sleep 1
	ds_write2_b32 v138, v98, v99 offset0:65 offset1:67
	s_sleep 1
	ds_write2_b32 v139, v90, v91 offset0:64 offset1:66
	s_sleep 1
	ds_write2_b32 v138, v100, v101 offset0:33 offset1:35
	s_sleep 1
	ds_write2_b32 v139, v92, v93 offset0:32 offset1:34
	s_sleep 1
	ds_write2_b32 v138, v102, v103 offset0:97 offset1:99
	s_sleep 1
	ds_write2_b32 v139, v94, v95 offset0:96 offset1:98
	s_sleep 1
	ds_write2_b32 v142, v104, v105 offset1:36
	s_sleep 1
	s_cmp_lg_u32 s7, 4
	s_cbranch_scc1 .Lsc_nokb1
	s_and_saveexec_b64 s[68:69], s[12:13]
	ds_write_b128 v158, v[88:91] offset:0
	ds_write_b128 v158, v[92:95] offset:128
	s_mov_b64 exec, s[68:69]
.Lsc_nokb1:
	s_add_i32 s6, s6, 1
	v_add_u32_e32 v146, 1, v146
	s_waitcnt lgkmcnt(0)
	ds_write_b32 v145, v146
	s_waitcnt vmcnt(10)
	v_lshlrev_b32_e32 v64, 16, v54
	v_and_b32_e32 v65, 0xffff0000, v54
	v_lshlrev_b32_e32 v66, 16, v55
	v_and_b32_e32 v67, 0xffff0000, v55
	v_lshlrev_b32_e32 v68, 16, v56
	v_and_b32_e32 v69, 0xffff0000, v56
	v_lshlrev_b32_e32 v70, 16, v57
	v_and_b32_e32 v71, 0xffff0000, v57
	ds_write_b128 v153, v[64:67]
	s_sleep 1
	ds_write_b128 v153, v[68:71] offset:128
	s_waitcnt lgkmcnt(0)
	ds_read_b32 v124, v154 offset:0
	ds_read_b32 v125, v154 offset:256
	ds_read_b32 v126, v154 offset:512
	ds_read_b32 v127, v154 offset:768
	ds_read_b32 v128, v154 offset:1024
	ds_read_b32 v129, v154 offset:1280
	ds_read_b32 v130, v154 offset:1536
	ds_read_b32 v131, v154 offset:1792
	v_lshlrev_b32_e32 v108, 16, v50
	v_and_b32_e32 v109, 0xffff0000, v50
	v_lshlrev_b32_e32 v110, 16, v58
	v_and_b32_e32 v111, 0xffff0000, v58
	v_lshlrev_b32_e32 v96, 16, v46
	v_and_b32_e32 v97, 0xffff0000, v46
	v_pk_mul_f32 v[114:115], v[12:13], v[108:109]
	v_pk_fma_f32 v[112:113], v[20:21], v[110:111], v[190:191]
	v_pk_mul_f32 v[88:89], v[62:63], v[114:115] op_sel_hi:[0,1]
	v_pk_mul_f32 v[72:73], v[112:113], v[108:109]
	v_pk_mul_f32 v[80:81], v[88:89], v[110:111]
	v_lshlrev_b32_e32 v108, 16, v51
	v_and_b32_e32 v109, 0xffff0000, v51
	v_lshlrev_b32_e32 v110, 16, v59
	v_and_b32_e32 v111, 0xffff0000, v59
	v_lshlrev_b32_e32 v98, 16, v47
	v_and_b32_e32 v99, 0xffff0000, v47
	v_pk_mul_f32 v[114:115], v[14:15], v[108:109]
	v_pk_fma_f32 v[112:113], v[22:23], v[110:111], v[192:193]
	v_pk_mul_f32 v[90:91], v[62:63], v[114:115] op_sel_hi:[0,1]
	v_pk_mul_f32 v[74:75], v[112:113], v[108:109]
	v_pk_mul_f32 v[82:83], v[90:91], v[110:111]
	v_lshlrev_b32_e32 v108, 16, v52
	v_and_b32_e32 v109, 0xffff0000, v52
	v_lshlrev_b32_e32 v110, 16, v60
	v_and_b32_e32 v111, 0xffff0000, v60
	v_lshlrev_b32_e32 v100, 16, v48
	v_and_b32_e32 v101, 0xffff0000, v48
	v_pk_mul_f32 v[114:115], v[16:17], v[108:109]
	v_pk_fma_f32 v[112:113], v[24:25], v[110:111], v[194:195]
	v_pk_mul_f32 v[92:93], v[62:63], v[114:115] op_sel_hi:[0,1]
	v_pk_mul_f32 v[76:77], v[112:113], v[108:109]
	v_pk_mul_f32 v[84:85], v[92:93], v[110:111]
	v_lshlrev_b32_e32 v108, 16, v53
	v_and_b32_e32 v109, 0xffff0000, v53
	v_lshlrev_b32_e32 v110, 16, v61
	v_and_b32_e32 v111, 0xffff0000, v61
	v_lshlrev_b32_e32 v102, 16, v49
	v_and_b32_e32 v103, 0xffff0000, v49
	v_pk_mul_f32 v[114:115], v[18:19], v[108:109]
	v_pk_fma_f32 v[112:113], v[26:27], v[110:111], v[196:197]
	v_pk_mul_f32 v[94:95], v[62:63], v[114:115] op_sel_hi:[0,1]
	v_pk_mul_f32 v[78:79], v[112:113], v[108:109]
	v_pk_mul_f32 v[86:87], v[94:95], v[110:111]
	v_lshlrev_b32_e32 v104, 16, v63
	v_and_b32_e32 v105, 0xffff0000, v63
	s_waitcnt lgkmcnt(0)
	v_add_f32_e32 v125, v124, v125
	v_add_f32_e32 v126, v125, v126
	v_add_f32_e32 v127, v126, v127
	v_add_f32_e32 v128, v127, v128
	v_add_f32_e32 v129, v128, v129
	v_add_f32_e32 v130, v129, v130
	v_add_f32_e32 v131, v130, v131
	s_and_b32 s72, s6, 3
	s_lshl_b32 s72, s72, 10
	v_add_u32_e32 v182, s72, v180
	v_add_u32_e32 v183, s72, v181
	v_mul_f32_e32 v189, 0x3fb8aa3b, v131
	ds_write_b32 v182, v189
	v_add_u32_e32 v184, 1, v146
	s_waitcnt lgkmcnt(0)
	ds_write_b32 v162, v184
	s_add_u32 s73, s6, 1
	s_mov_b32 s69, 0x100000

.Lsc_gf_go2:
	ds_read_b32 v185, v183
	ds_read_b32 v186, v183 offset:256
	ds_read_b32 v187, v183 offset:512
	s_waitcnt lgkmcnt(0)
	v_and_b32_e32 v185, v174, v185
	v_and_b32_e32 v186, v175, v186
	v_and_b32_e32 v187, v176, v187
	v_add_f32_e32 v185, v185, v186
	v_add_f32_e32 v185, v185, v187
	v_fma_f32 v124, v124, s14, v185
	v_fma_f32 v125, v125, s14, v185
	v_fma_f32 v126, v126, s14, v185
	v_fma_f32 v127, v127, s14, v185
	v_fma_f32 v128, v128, s14, v185
	v_fma_f32 v129, v129, s14, v185
	v_fma_f32 v130, v130, s14, v185
	v_fma_f32 v131, v131, s14, v185
	v_exp_f32_e64 v188, -v185
	v_exp_f32_e64 v124, -v124
	v_exp_f32_e64 v125, -v125
	v_exp_f32_e64 v126, -v126
	v_exp_f32_e64 v127, -v127
	v_exp_f32_e64 v128, -v128
	v_exp_f32_e64 v129, -v129
	v_exp_f32_e64 v130, -v130
	v_exp_f32_e64 v131, -v131
	s_nop 0
	ds_write_b32 v155, v188
	ds_write_b32 v155, v124 offset:256
	ds_write_b32 v155, v125 offset:512
	ds_write_b32 v155, v126 offset:768
	s_sleep 1
	ds_write_b32 v155, v127 offset:1024
	ds_write_b32 v155, v128 offset:1280
	ds_write_b32 v155, v129 offset:1536
	s_sleep 1
	ds_write_b32 v155, v130 offset:1792
	ds_write_b32 v155, v131 offset:2048
	v_mov_b32_e32 v161, v131
	s_waitcnt lgkmcnt(0)
	ds_read_b128 v[64:67], v153 offset:2048
	ds_read_b128 v[68:71], v153 offset:2176
	ds_read_b128 v[116:119], v153 offset:2304
	ds_read_b128 v[120:123], v153 offset:2432
	s_waitcnt lgkmcnt(0)
	v_rcp_f32_e32 v124, v116
	v_rcp_f32_e32 v125, v117
	v_rcp_f32_e32 v126, v118
	v_rcp_f32_e32 v127, v119
	v_rcp_f32_e32 v128, v120
	v_rcp_f32_e32 v129, v121
	v_rcp_f32_e32 v130, v122
	v_rcp_f32_e32 v131, v123
	s_nop 1
	v_pk_mul_f32 v[72:73], v[72:73], v[124:125]
	v_pk_mul_f32 v[80:81], v[80:81], v[124:125]
	v_pk_mul_f32 v[88:89], v[88:89], v[64:65]
	v_pk_mul_f32 v[96:97], v[96:97], v[116:117]
	v_pk_mul_f32 v[74:75], v[74:75], v[126:127]
	v_pk_mul_f32 v[82:83], v[82:83], v[126:127]
	v_pk_mul_f32 v[90:91], v[90:91], v[66:67]
	v_pk_mul_f32 v[98:99], v[98:99], v[118:119]
	v_pk_mul_f32 v[76:77], v[76:77], v[128:129]
	v_pk_mul_f32 v[84:85], v[84:85], v[128:129]
	v_pk_mul_f32 v[92:93], v[92:93], v[68:69]
	v_pk_mul_f32 v[100:101], v[100:101], v[120:121]
	v_pk_mul_f32 v[78:79], v[78:79], v[130:131]
	v_pk_mul_f32 v[86:87], v[86:87], v[130:131]
	v_pk_mul_f32 v[94:95], v[94:95], v[70:71]
	v_pk_mul_f32 v[102:103], v[102:103], v[122:123]
	global_load_dwordx2 v[46:47], v5, s[36:37]
	global_load_dwordx2 v[48:49], v5, s[36:37] offset:64
	global_load_dwordx2 v[50:51], v5, s[38:39]
	global_load_dwordx2 v[52:53], v5, s[38:39] offset:64
	global_load_dwordx2 v[54:55], v5, s[40:41]
	global_load_dwordx2 v[56:57], v5, s[40:41] offset:64
	global_load_dwordx2 v[58:59], v5, s[42:43]
	global_load_dwordx2 v[60:61], v5, s[42:43] offset:64
	global_load_dword v62, v6, s[46:47]
	global_load_dword v63, v9, s[44:45]
	v_add_u32_e32 v5, s54, v5
	v_add_u32_e32 v6, s55, v6
	v_add_u32_e32 v9, s54, v9
	ds_write_b32 v159, v161 offset:34816
	s_sleep 1
	ds_write_b128 v8, v[72:75] offset:34816
	s_sleep 1
	ds_write_b128 v8, v[76:79] offset:34944
	s_sleep 1
	ds_write_b128 v8, v[80:83] offset:35072
	s_sleep 1
	ds_write_b128 v8, v[84:87] offset:35200
	s_sleep 1
	ds_write2_b32 v140, v96, v97 offset0:1 offset1:3
	s_sleep 1
	ds_write2_b32 v141, v88, v89 offset0:0 offset1:2
	s_sleep 1
	ds_write2_b32 v140, v98, v99 offset0:65 offset1:67
	s_sleep 1
	ds_write2_b32 v141, v90, v91 offset0:64 offset1:66
	s_sleep 1
	ds_write2_b32 v140, v100, v101 offset0:33 offset1:35
	s_sleep 1
	ds_write2_b32 v141, v92, v93 offset0:32 offset1:34
	s_sleep 1
	ds_write2_b32 v140, v102, v103 offset0:97 offset1:99
	s_sleep 1
	ds_write2_b32 v141, v94, v95 offset0:96 offset1:98
	s_sleep 1
	ds_write2_b32 v143, v104, v105 offset1:36
	s_sleep 1
	s_cmp_lg_u32 s7, 4
	s_cbranch_scc1 .Lsc_nokb2
	s_and_saveexec_b64 s[68:69], s[12:13]
	ds_write_b128 v158, v[88:91] offset:34816
	ds_write_b128 v158, v[92:95] offset:34944
	s_mov_b64 exec, s[68:69]

.Lsc_G_loop:
	s_waitcnt vmcnt(10)
	v_lshlrev_b32_e32 v64, 16, v36
	v_and_b32_e32 v65, 0xffff0000, v36
	v_lshlrev_b32_e32 v66, 16, v37
	v_and_b32_e32 v67, 0xffff0000, v37
	v_lshlrev_b32_e32 v68, 16, v38
	v_and_b32_e32 v69, 0xffff0000, v38
	v_lshlrev_b32_e32 v70, 16, v39
	v_and_b32_e32 v71, 0xffff0000, v39
	ds_write_b128 v153, v[64:67]
	s_sleep 1
	ds_write_b128 v153, v[68:71] offset:128
	s_waitcnt lgkmcnt(0)
	ds_read_b32 v124, v154 offset:0
	ds_read_b32 v125, v154 offset:256
	ds_read_b32 v126, v154 offset:512
	ds_read_b32 v127, v154 offset:768
	ds_read_b32 v128, v154 offset:1024
	ds_read_b32 v129, v154 offset:1280
	ds_read_b32 v130, v154 offset:1536
	ds_read_b32 v131, v154 offset:1792
	v_lshlrev_b32_e32 v108, 16, v32
	v_and_b32_e32 v109, 0xffff0000, v32
	v_lshlrev_b32_e32 v110, 16, v40
	v_and_b32_e32 v111, 0xffff0000, v40
	v_lshlrev_b32_e32 v96, 16, v28
	v_and_b32_e32 v97, 0xffff0000, v28
	v_pk_mul_f32 v[114:115], v[12:13], v[108:109]
	v_pk_fma_f32 v[112:113], v[20:21], v[110:111], v[190:191]
	v_pk_mul_f32 v[88:89], v[44:45], v[114:115] op_sel_hi:[0,1]
	v_pk_mul_f32 v[72:73], v[112:113], v[108:109]
	v_pk_mul_f32 v[80:81], v[88:89], v[110:111]
	v_lshlrev_b32_e32 v108, 16, v33
	v_and_b32_e32 v109, 0xffff0000, v33
	v_lshlrev_b32_e32 v110, 16, v41
	v_and_b32_e32 v111, 0xffff0000, v41
	v_lshlrev_b32_e32 v98, 16, v29
	v_and_b32_e32 v99, 0xffff0000, v29
	v_pk_mul_f32 v[114:115], v[14:15], v[108:109]
	v_pk_fma_f32 v[112:113], v[22:23], v[110:111], v[192:193]
	v_pk_mul_f32 v[90:91], v[44:45], v[114:115] op_sel_hi:[0,1]
	v_pk_mul_f32 v[74:75], v[112:113], v[108:109]
	v_pk_mul_f32 v[82:83], v[90:91], v[110:111]
	v_lshlrev_b32_e32 v108, 16, v34
	v_and_b32_e32 v109, 0xffff0000, v34
	v_lshlrev_b32_e32 v110, 16, v42
	v_and_b32_e32 v111, 0xffff0000, v42
	v_lshlrev_b32_e32 v100, 16, v30
	v_and_b32_e32 v101, 0xffff0000, v30
	v_pk_mul_f32 v[114:115], v[16:17], v[108:109]
	v_pk_fma_f32 v[112:113], v[24:25], v[110:111], v[194:195]
	v_pk_mul_f32 v[92:93], v[44:45], v[114:115] op_sel_hi:[0,1]
	v_pk_mul_f32 v[76:77], v[112:113], v[108:109]
	v_pk_mul_f32 v[84:85], v[92:93], v[110:111]
	v_lshlrev_b32_e32 v108, 16, v35
	v_and_b32_e32 v109, 0xffff0000, v35
	v_lshlrev_b32_e32 v110, 16, v43
	v_and_b32_e32 v111, 0xffff0000, v43
	v_lshlrev_b32_e32 v102, 16, v31
	v_and_b32_e32 v103, 0xffff0000, v31
	v_pk_mul_f32 v[114:115], v[18:19], v[108:109]
	v_pk_fma_f32 v[112:113], v[26:27], v[110:111], v[196:197]
	v_pk_mul_f32 v[94:95], v[44:45], v[114:115] op_sel_hi:[0,1]
	v_pk_mul_f32 v[78:79], v[112:113], v[108:109]
	v_pk_mul_f32 v[86:87], v[94:95], v[110:111]
	v_lshlrev_b32_e32 v104, 16, v45
	v_and_b32_e32 v105, 0xffff0000, v45
	s_waitcnt lgkmcnt(0)
	v_add_f32_e32 v125, v124, v125
	v_add_f32_e32 v126, v125, v126
	v_add_f32_e32 v127, v126, v127
	v_add_f32_e32 v128, v127, v128
	v_add_f32_e32 v129, v128, v129
	v_add_f32_e32 v130, v129, v130
	v_add_f32_e32 v131, v130, v131
	s_and_b32 s72, s6, 3
	s_lshl_b32 s72, s72, 10
	v_add_u32_e32 v182, s72, v180
	v_add_u32_e32 v183, s72, v181
	v_mul_f32_e32 v189, 0x3fb8aa3b, v131
	ds_write_b32 v182, v189
	v_add_u32_e32 v184, 1, v146
	s_waitcnt lgkmcnt(0)
	ds_write_b32 v162, v184
	s_add_u32 s73, s6, 1
	s_mov_b32 s69, 0x100000

.Lsc_gf_go3:
	ds_read_b32 v185, v183
	ds_read_b32 v186, v183 offset:256
	ds_read_b32 v187, v183 offset:512
	s_waitcnt lgkmcnt(0)
	v_and_b32_e32 v185, v174, v185
	v_and_b32_e32 v186, v175, v186
	v_and_b32_e32 v187, v176, v187
	v_add_f32_e32 v185, v185, v186
	v_add_f32_e32 v185, v185, v187
	v_fma_f32 v124, v124, s14, v185
	v_fma_f32 v125, v125, s14, v185
	v_fma_f32 v126, v126, s14, v185
	v_fma_f32 v127, v127, s14, v185
	v_fma_f32 v128, v128, s14, v185
	v_fma_f32 v129, v129, s14, v185
	v_fma_f32 v130, v130, s14, v185
	v_fma_f32 v131, v131, s14, v185
	v_exp_f32_e64 v188, -v185
	v_exp_f32_e64 v124, -v124
	v_exp_f32_e64 v125, -v125
	v_exp_f32_e64 v126, -v126
	v_exp_f32_e64 v127, -v127
	v_exp_f32_e64 v128, -v128
	v_exp_f32_e64 v129, -v129
	v_exp_f32_e64 v130, -v130
	v_exp_f32_e64 v131, -v131
	s_nop 0
	ds_write_b32 v155, v188
	ds_write_b32 v155, v124 offset:256
	ds_write_b32 v155, v125 offset:512
	ds_write_b32 v155, v126 offset:768
	s_sleep 1
	ds_write_b32 v155, v127 offset:1024
	ds_write_b32 v155, v128 offset:1280
	ds_write_b32 v155, v129 offset:1536
	s_sleep 1
	ds_write_b32 v155, v130 offset:1792
	ds_write_b32 v155, v131 offset:2048
	v_mov_b32_e32 v161, v131
	s_waitcnt lgkmcnt(0)
	ds_read_b128 v[64:67], v153 offset:2048
	ds_read_b128 v[68:71], v153 offset:2176
	ds_read_b128 v[116:119], v153 offset:2304
	ds_read_b128 v[120:123], v153 offset:2432
	s_waitcnt lgkmcnt(0)
	v_rcp_f32_e32 v124, v116
	v_rcp_f32_e32 v125, v117
	v_rcp_f32_e32 v126, v118
	v_rcp_f32_e32 v127, v119
	v_rcp_f32_e32 v128, v120
	v_rcp_f32_e32 v129, v121
	v_rcp_f32_e32 v130, v122
	v_rcp_f32_e32 v131, v123
	s_nop 1
	v_pk_mul_f32 v[72:73], v[72:73], v[124:125]
	v_pk_mul_f32 v[80:81], v[80:81], v[124:125]
	v_pk_mul_f32 v[88:89], v[88:89], v[64:65]
	v_pk_mul_f32 v[96:97], v[96:97], v[116:117]
	v_pk_mul_f32 v[74:75], v[74:75], v[126:127]
	v_pk_mul_f32 v[82:83], v[82:83], v[126:127]
	v_pk_mul_f32 v[90:91], v[90:91], v[66:67]
	v_pk_mul_f32 v[98:99], v[98:99], v[118:119]
	v_pk_mul_f32 v[76:77], v[76:77], v[128:129]
	v_pk_mul_f32 v[84:85], v[84:85], v[128:129]
	v_pk_mul_f32 v[92:93], v[92:93], v[68:69]
	v_pk_mul_f32 v[100:101], v[100:101], v[120:121]
	v_pk_mul_f32 v[78:79], v[78:79], v[130:131]
	v_pk_mul_f32 v[86:87], v[86:87], v[130:131]
	v_pk_mul_f32 v[94:95], v[94:95], v[70:71]
	v_pk_mul_f32 v[102:103], v[102:103], v[122:123]
	global_load_dwordx2 v[28:29], v5, s[36:37]
	global_load_dwordx2 v[30:31], v5, s[36:37] offset:64
	global_load_dwordx2 v[32:33], v5, s[38:39]
	global_load_dwordx2 v[34:35], v5, s[38:39] offset:64
	global_load_dwordx2 v[36:37], v5, s[40:41]
	global_load_dwordx2 v[38:39], v5, s[40:41] offset:64
	global_load_dwordx2 v[40:41], v5, s[42:43]
	global_load_dwordx2 v[42:43], v5, s[42:43] offset:64
	global_load_dword v44, v6, s[46:47]
	global_load_dword v45, v9, s[44:45]
	v_add_u32_e32 v5, s54, v5
	v_add_u32_e32 v6, s55, v6
	v_add_u32_e32 v9, s54, v9
	s_sub_u32 s65, s6, 1
	ds_read_b128 v[148:151], v144
	s_waitcnt lgkmcnt(0)
	v_min_u32_e32 v148, v148, v149
	v_min3_u32 v148, v148, v150, v151
	s_nop 1
	v_readfirstlane_b32 s68, v148
	s_cmp_ge_u32 s68, s65
	s_cbranch_scc1 .Lsc_G_gom0
	s_mov_b32 s69, 0x100000

.Lsc_G_gom0:
	ds_write_b32 v159, v161 offset:0
	s_sleep 1
	ds_write_b128 v8, v[72:75] offset:0
	s_sleep 1
	ds_write_b128 v8, v[76:79] offset:128
	s_sleep 1
	ds_write_b128 v8, v[80:83] offset:256
	s_sleep 1
	ds_write_b128 v8, v[84:87] offset:384
	s_sleep 1
	ds_write2_b32 v138, v96, v97 offset0:1 offset1:3
	s_sleep 1
	ds_write2_b32 v139, v88, v89 offset0:0 offset1:2
	s_sleep 1
	ds_write2_b32 v138, v98, v99 offset0:65 offset1:67
	s_sleep 1
	ds_write2_b32 v139, v90, v91 offset0:64 offset1:66
	s_sleep 1
	ds_write2_b32 v138, v100, v101 offset0:33 offset1:35
	s_sleep 1
	ds_write2_b32 v139, v92, v93 offset0:32 offset1:34
	s_sleep 1
	ds_write2_b32 v138, v102, v103 offset0:97 offset1:99
	s_sleep 1
	ds_write2_b32 v139, v94, v95 offset0:96 offset1:98
	s_sleep 1
	ds_write2_b32 v142, v104, v105 offset1:36
	s_sleep 1
	s_cmp_lg_u32 s7, 4
	s_cbranch_scc1 .Lsc_nokb3
	s_and_saveexec_b64 s[68:69], s[12:13]
	ds_write_b128 v158, v[88:91] offset:0
	ds_write_b128 v158, v[92:95] offset:128
	s_mov_b64 exec, s[68:69]
.Lsc_nokb3:
	ds_read_b128 v[106:109], v2 offset:0
	s_sleep 1
	ds_read_b128 v[122:125], v2 offset:16384
	s_sleep 1
	ds_read_b128 v[110:113], v3 offset:0
	s_sleep 1
	ds_read_b128 v[126:129], v3 offset:16384
	s_sleep 1
	ds_read_b128 v[114:117], v4 offset:0
	s_sleep 1
	ds_read_b128 v[130:133], v4 offset:16384
	s_sleep 1
	ds_read_b128 v[118:121], v10 offset:0
	s_sleep 1
	ds_read_b128 v[134:137], v10 offset:16384
	s_sleep 1
	s_waitcnt lgkmcnt(0)
	v_pk_add_f32 v[106:107], v[106:107], v[108:109]
	v_pk_add_f32 v[110:111], v[110:111], v[112:113]
	v_pk_add_f32 v[114:115], v[114:115], v[116:117]
	v_pk_add_f32 v[118:119], v[118:119], v[120:121]
	v_pk_add_f32 v[106:107], v[106:107], v[110:111]
	v_pk_add_f32 v[114:115], v[114:115], v[118:119]
	v_pk_add_f32 v[106:107], v[106:107], v[114:115]
	v_add_f32_e32 v64, v106, v107
	v_pk_add_f32 v[122:123], v[122:123], v[124:125]
	v_pk_add_f32 v[126:127], v[126:127], v[128:129]
	v_pk_add_f32 v[130:131], v[130:131], v[132:133]
	v_pk_add_f32 v[134:135], v[134:135], v[136:137]
	v_pk_add_f32 v[122:123], v[122:123], v[126:127]
	v_pk_add_f32 v[130:131], v[130:131], v[134:135]
	v_pk_add_f32 v[122:123], v[122:123], v[130:131]
	v_add_f32_e32 v65, v122, v123
	global_store_dword v7, v64, s[48:49]
	global_store_dword v165, v65, s[48:49]
	v_add_u32_e32 v7, s64, v7
	v_add_u32_e32 v165, s64, v165
	s_add_i32 s6, s6, 1
	v_add_u32_e32 v146, 1, v146
	s_waitcnt lgkmcnt(0)
	ds_write_b32 v145, v146
	s_waitcnt vmcnt(10)
	v_lshlrev_b32_e32 v64, 16, v54
	v_and_b32_e32 v65, 0xffff0000, v54
	v_lshlrev_b32_e32 v66, 16, v55
	v_and_b32_e32 v67, 0xffff0000, v55
	v_lshlrev_b32_e32 v68, 16, v56
	v_and_b32_e32 v69, 0xffff0000, v56
	v_lshlrev_b32_e32 v70, 16, v57
	v_and_b32_e32 v71, 0xffff0000, v57
	ds_write_b128 v153, v[64:67]
	s_sleep 1
	ds_write_b128 v153, v[68:71] offset:128
	s_waitcnt lgkmcnt(0)
	ds_read_b32 v124, v154 offset:0
	ds_read_b32 v125, v154 offset:256
	ds_read_b32 v126, v154 offset:512
	ds_read_b32 v127, v154 offset:768
	ds_read_b32 v128, v154 offset:1024
	ds_read_b32 v129, v154 offset:1280
	ds_read_b32 v130, v154 offset:1536
	ds_read_b32 v131, v154 offset:1792
	v_lshlrev_b32_e32 v108, 16, v50
	v_and_b32_e32 v109, 0xffff0000, v50
	v_lshlrev_b32_e32 v110, 16, v58
	v_and_b32_e32 v111, 0xffff0000, v58
	v_lshlrev_b32_e32 v96, 16, v46
	v_and_b32_e32 v97, 0xffff0000, v46
	v_pk_mul_f32 v[114:115], v[12:13], v[108:109]
	v_pk_fma_f32 v[112:113], v[20:21], v[110:111], v[190:191]
	v_pk_mul_f32 v[88:89], v[62:63], v[114:115] op_sel_hi:[0,1]
	v_pk_mul_f32 v[72:73], v[112:113], v[108:109]
	v_pk_mul_f32 v[80:81], v[88:89], v[110:111]
	v_lshlrev_b32_e32 v108, 16, v51
	v_and_b32_e32 v109, 0xffff0000, v51
	v_lshlrev_b32_e32 v110, 16, v59
	v_and_b32_e32 v111, 0xffff0000, v59
	v_lshlrev_b32_e32 v98, 16, v47
	v_and_b32_e32 v99, 0xffff0000, v47
	v_pk_mul_f32 v[114:115], v[14:15], v[108:109]
	v_pk_fma_f32 v[112:113], v[22:23], v[110:111], v[192:193]
	v_pk_mul_f32 v[90:91], v[62:63], v[114:115] op_sel_hi:[0,1]
	v_pk_mul_f32 v[74:75], v[112:113], v[108:109]
	v_pk_mul_f32 v[82:83], v[90:91], v[110:111]
	v_lshlrev_b32_e32 v108, 16, v52
	v_and_b32_e32 v109, 0xffff0000, v52
	v_lshlrev_b32_e32 v110, 16, v60
	v_and_b32_e32 v111, 0xffff0000, v60
	v_lshlrev_b32_e32 v100, 16, v48
	v_and_b32_e32 v101, 0xffff0000, v48
	v_pk_mul_f32 v[114:115], v[16:17], v[108:109]
	v_pk_fma_f32 v[112:113], v[24:25], v[110:111], v[194:195]
	v_pk_mul_f32 v[92:93], v[62:63], v[114:115] op_sel_hi:[0,1]
	v_pk_mul_f32 v[76:77], v[112:113], v[108:109]
	v_pk_mul_f32 v[84:85], v[92:93], v[110:111]
	v_lshlrev_b32_e32 v108, 16, v53
	v_and_b32_e32 v109, 0xffff0000, v53
	v_lshlrev_b32_e32 v110, 16, v61
	v_and_b32_e32 v111, 0xffff0000, v61
	v_lshlrev_b32_e32 v102, 16, v49
	v_and_b32_e32 v103, 0xffff0000, v49
	v_pk_mul_f32 v[114:115], v[18:19], v[108:109]
	v_pk_fma_f32 v[112:113], v[26:27], v[110:111], v[196:197]
	v_pk_mul_f32 v[94:95], v[62:63], v[114:115] op_sel_hi:[0,1]
	v_pk_mul_f32 v[78:79], v[112:113], v[108:109]
	v_pk_mul_f32 v[86:87], v[94:95], v[110:111]
	v_lshlrev_b32_e32 v104, 16, v63
	v_and_b32_e32 v105, 0xffff0000, v63
	s_waitcnt lgkmcnt(0)
	v_add_f32_e32 v125, v124, v125
	v_add_f32_e32 v126, v125, v126
	v_add_f32_e32 v127, v126, v127
	v_add_f32_e32 v128, v127, v128
	v_add_f32_e32 v129, v128, v129
	v_add_f32_e32 v130, v129, v130
	v_add_f32_e32 v131, v130, v131
	s_and_b32 s72, s6, 3
	s_lshl_b32 s72, s72, 10
	v_add_u32_e32 v182, s72, v180
	v_add_u32_e32 v183, s72, v181
	v_mul_f32_e32 v189, 0x3fb8aa3b, v131
	ds_write_b32 v182, v189
	v_add_u32_e32 v184, 1, v146
	s_waitcnt lgkmcnt(0)
	ds_write_b32 v162, v184
	s_add_u32 s73, s6, 1
	s_mov_b32 s69, 0x100000

.Lsc_gf_go4:
	ds_read_b32 v185, v183
	ds_read_b32 v186, v183 offset:256
	ds_read_b32 v187, v183 offset:512
	s_waitcnt lgkmcnt(0)
	v_and_b32_e32 v185, v174, v185
	v_and_b32_e32 v186, v175, v186
	v_and_b32_e32 v187, v176, v187
	v_add_f32_e32 v185, v185, v186
	v_add_f32_e32 v185, v185, v187
	v_fma_f32 v124, v124, s14, v185
	v_fma_f32 v125, v125, s14, v185
	v_fma_f32 v126, v126, s14, v185
	v_fma_f32 v127, v127, s14, v185
	v_fma_f32 v128, v128, s14, v185
	v_fma_f32 v129, v129, s14, v185
	v_fma_f32 v130, v130, s14, v185
	v_fma_f32 v131, v131, s14, v185
	v_exp_f32_e64 v188, -v185
	v_exp_f32_e64 v124, -v124
	v_exp_f32_e64 v125, -v125
	v_exp_f32_e64 v126, -v126
	v_exp_f32_e64 v127, -v127
	v_exp_f32_e64 v128, -v128
	v_exp_f32_e64 v129, -v129
	v_exp_f32_e64 v130, -v130
	v_exp_f32_e64 v131, -v131
	s_nop 0
	ds_write_b32 v155, v188
	ds_write_b32 v155, v124 offset:256
	ds_write_b32 v155, v125 offset:512
	ds_write_b32 v155, v126 offset:768
	s_sleep 1
	ds_write_b32 v155, v127 offset:1024
	ds_write_b32 v155, v128 offset:1280
	ds_write_b32 v155, v129 offset:1536
	s_sleep 1
	ds_write_b32 v155, v130 offset:1792
	ds_write_b32 v155, v131 offset:2048
	v_mov_b32_e32 v161, v131
	s_waitcnt lgkmcnt(0)
	ds_read_b128 v[64:67], v153 offset:2048
	ds_read_b128 v[68:71], v153 offset:2176
	ds_read_b128 v[116:119], v153 offset:2304
	ds_read_b128 v[120:123], v153 offset:2432
	s_waitcnt lgkmcnt(0)
	v_rcp_f32_e32 v124, v116
	v_rcp_f32_e32 v125, v117
	v_rcp_f32_e32 v126, v118
	v_rcp_f32_e32 v127, v119
	v_rcp_f32_e32 v128, v120
	v_rcp_f32_e32 v129, v121
	v_rcp_f32_e32 v130, v122
	v_rcp_f32_e32 v131, v123
	s_nop 1
	v_pk_mul_f32 v[72:73], v[72:73], v[124:125]
	v_pk_mul_f32 v[80:81], v[80:81], v[124:125]
	v_pk_mul_f32 v[88:89], v[88:89], v[64:65]
	v_pk_mul_f32 v[96:97], v[96:97], v[116:117]
	v_pk_mul_f32 v[74:75], v[74:75], v[126:127]
	v_pk_mul_f32 v[82:83], v[82:83], v[126:127]
	v_pk_mul_f32 v[90:91], v[90:91], v[66:67]
	v_pk_mul_f32 v[98:99], v[98:99], v[118:119]
	v_pk_mul_f32 v[76:77], v[76:77], v[128:129]
	v_pk_mul_f32 v[84:85], v[84:85], v[128:129]
	v_pk_mul_f32 v[92:93], v[92:93], v[68:69]
	v_pk_mul_f32 v[100:101], v[100:101], v[120:121]
	v_pk_mul_f32 v[78:79], v[78:79], v[130:131]
	v_pk_mul_f32 v[86:87], v[86:87], v[130:131]
	v_pk_mul_f32 v[94:95], v[94:95], v[70:71]
	v_pk_mul_f32 v[102:103], v[102:103], v[122:123]
	global_load_dwordx2 v[46:47], v5, s[36:37]
	global_load_dwordx2 v[48:49], v5, s[36:37] offset:64
	global_load_dwordx2 v[50:51], v5, s[38:39]
	global_load_dwordx2 v[52:53], v5, s[38:39] offset:64
	global_load_dwordx2 v[54:55], v5, s[40:41]
	global_load_dwordx2 v[56:57], v5, s[40:41] offset:64
	global_load_dwordx2 v[58:59], v5, s[42:43]
	global_load_dwordx2 v[60:61], v5, s[42:43] offset:64
	global_load_dword v62, v6, s[46:47]
	global_load_dword v63, v9, s[44:45]
	v_add_u32_e32 v5, s54, v5
	v_add_u32_e32 v6, s55, v6
	v_add_u32_e32 v9, s54, v9
	s_sub_u32 s65, s6, 1
	ds_read_b128 v[148:151], v144
	s_waitcnt lgkmcnt(0)
	v_min_u32_e32 v148, v148, v149
	v_min3_u32 v148, v148, v150, v151
	s_nop 1
	v_readfirstlane_b32 s68, v148
	s_cmp_ge_u32 s68, s65
	s_cbranch_scc1 .Lsc_G_gom1
	s_mov_b32 s69, 0x100000

.Lsc_G_gom1:
	ds_write_b32 v159, v161 offset:34816
	s_sleep 1
	ds_write_b128 v8, v[72:75] offset:34816
	s_sleep 1
	ds_write_b128 v8, v[76:79] offset:34944
	s_sleep 1
	ds_write_b128 v8, v[80:83] offset:35072
	s_sleep 1
	ds_write_b128 v8, v[84:87] offset:35200
	s_sleep 1
	ds_write2_b32 v140, v96, v97 offset0:1 offset1:3
	s_sleep 1
	ds_write2_b32 v141, v88, v89 offset0:0 offset1:2
	s_sleep 1
	ds_write2_b32 v140, v98, v99 offset0:65 offset1:67
	s_sleep 1
	ds_write2_b32 v141, v90, v91 offset0:64 offset1:66
	s_sleep 1
	ds_write2_b32 v140, v100, v101 offset0:33 offset1:35
	s_sleep 1
	ds_write2_b32 v141, v92, v93 offset0:32 offset1:34
	s_sleep 1
	ds_write2_b32 v140, v102, v103 offset0:97 offset1:99
	s_sleep 1
	ds_write2_b32 v141, v94, v95 offset0:96 offset1:98
	s_sleep 1
	ds_write2_b32 v143, v104, v105 offset1:36
	s_sleep 1
	s_cmp_lg_u32 s7, 4
	s_cbranch_scc1 .Lsc_nokb4
	s_and_saveexec_b64 s[68:69], s[12:13]
	ds_write_b128 v158, v[88:91] offset:34816
	ds_write_b128 v158, v[92:95] offset:34944
	s_mov_b64 exec, s[68:69]
.Lsc_nokb4:
	ds_read_b128 v[106:109], v2 offset:32768
	s_sleep 1
	ds_read_b128 v[122:125], v2 offset:49152
	s_sleep 1
	ds_read_b128 v[110:113], v3 offset:32768
	s_sleep 1
	ds_read_b128 v[126:129], v3 offset:49152
	s_sleep 1
	ds_read_b128 v[114:117], v4 offset:32768
	s_sleep 1
	ds_read_b128 v[130:133], v4 offset:49152
	s_sleep 1
	ds_read_b128 v[118:121], v10 offset:32768
	s_sleep 1
	ds_read_b128 v[134:137], v10 offset:49152
	s_sleep 1
	s_waitcnt lgkmcnt(0)
	v_pk_add_f32 v[106:107], v[106:107], v[108:109]
	v_pk_add_f32 v[110:111], v[110:111], v[112:113]
	v_pk_add_f32 v[114:115], v[114:115], v[116:117]
	v_pk_add_f32 v[118:119], v[118:119], v[120:121]
	v_pk_add_f32 v[106:107], v[106:107], v[110:111]
	v_pk_add_f32 v[114:115], v[114:115], v[118:119]
	v_pk_add_f32 v[106:107], v[106:107], v[114:115]
	v_add_f32_e32 v64, v106, v107
	v_pk_add_f32 v[122:123], v[122:123], v[124:125]
	v_pk_add_f32 v[126:127], v[126:127], v[128:129]
	v_pk_add_f32 v[130:131], v[130:131], v[132:133]
	v_pk_add_f32 v[134:135], v[134:135], v[136:137]
	v_pk_add_f32 v[122:123], v[122:123], v[126:127]
	v_pk_add_f32 v[130:131], v[130:131], v[134:135]
	v_pk_add_f32 v[122:123], v[122:123], v[130:131]
	v_add_f32_e32 v65, v122, v123
	global_store_dword v7, v64, s[48:49]
	global_store_dword v165, v65, s[48:49]
	v_add_u32_e32 v7, s64, v7
	v_add_u32_e32 v165, s64, v165
	s_add_i32 s6, s6, 1
	v_add_u32_e32 v146, 1, v146
	s_waitcnt lgkmcnt(0)
	ds_write_b32 v145, v146
	s_cmp_lt_u32 s6, 0xfe
	s_cbranch_scc1 .Lsc_G_loop
	s_waitcnt vmcnt(10)
	v_lshlrev_b32_e32 v64, 16, v36
	v_and_b32_e32 v65, 0xffff0000, v36
	v_lshlrev_b32_e32 v66, 16, v37
	v_and_b32_e32 v67, 0xffff0000, v37
	v_lshlrev_b32_e32 v68, 16, v38
	v_and_b32_e32 v69, 0xffff0000, v38
	v_lshlrev_b32_e32 v70, 16, v39
	v_and_b32_e32 v71, 0xffff0000, v39
	ds_write_b128 v153, v[64:67]
	s_sleep 1
	ds_write_b128 v153, v[68:71] offset:128
	s_waitcnt lgkmcnt(0)
	ds_read_b32 v124, v154 offset:0
	ds_read_b32 v125, v154 offset:256
	ds_read_b32 v126, v154 offset:512
	ds_read_b32 v127, v154 offset:768
	ds_read_b32 v128, v154 offset:1024
	ds_read_b32 v129, v154 offset:1280
	ds_read_b32 v130, v154 offset:1536
	ds_read_b32 v131, v154 offset:1792
	v_lshlrev_b32_e32 v108, 16, v32
	v_and_b32_e32 v109, 0xffff0000, v32
	v_lshlrev_b32_e32 v110, 16, v40
	v_and_b32_e32 v111, 0xffff0000, v40
	v_lshlrev_b32_e32 v96, 16, v28
	v_and_b32_e32 v97, 0xffff0000, v28
	v_pk_mul_f32 v[114:115], v[12:13], v[108:109]
	v_pk_fma_f32 v[112:113], v[20:21], v[110:111], v[190:191]
	v_pk_mul_f32 v[88:89], v[44:45], v[114:115] op_sel_hi:[0,1]
	v_pk_mul_f32 v[72:73], v[112:113], v[108:109]
	v_pk_mul_f32 v[80:81], v[88:89], v[110:111]
	v_lshlrev_b32_e32 v108, 16, v33
	v_and_b32_e32 v109, 0xffff0000, v33
	v_lshlrev_b32_e32 v110, 16, v41
	v_and_b32_e32 v111, 0xffff0000, v41
	v_lshlrev_b32_e32 v98, 16, v29
	v_and_b32_e32 v99, 0xffff0000, v29
	v_pk_mul_f32 v[114:115], v[14:15], v[108:109]
	v_pk_fma_f32 v[112:113], v[22:23], v[110:111], v[192:193]
	v_pk_mul_f32 v[90:91], v[44:45], v[114:115] op_sel_hi:[0,1]
	v_pk_mul_f32 v[74:75], v[112:113], v[108:109]
	v_pk_mul_f32 v[82:83], v[90:91], v[110:111]
	v_lshlrev_b32_e32 v108, 16, v34
	v_and_b32_e32 v109, 0xffff0000, v34
	v_lshlrev_b32_e32 v110, 16, v42
	v_and_b32_e32 v111, 0xffff0000, v42
	v_lshlrev_b32_e32 v100, 16, v30
	v_and_b32_e32 v101, 0xffff0000, v30
	v_pk_mul_f32 v[114:115], v[16:17], v[108:109]
	v_pk_fma_f32 v[112:113], v[24:25], v[110:111], v[194:195]
	v_pk_mul_f32 v[92:93], v[44:45], v[114:115] op_sel_hi:[0,1]
	v_pk_mul_f32 v[76:77], v[112:113], v[108:109]
	v_pk_mul_f32 v[84:85], v[92:93], v[110:111]
	v_lshlrev_b32_e32 v108, 16, v35
	v_and_b32_e32 v109, 0xffff0000, v35
	v_lshlrev_b32_e32 v110, 16, v43
	v_and_b32_e32 v111, 0xffff0000, v43
	v_lshlrev_b32_e32 v102, 16, v31
	v_and_b32_e32 v103, 0xffff0000, v31
	v_pk_mul_f32 v[114:115], v[18:19], v[108:109]
	v_pk_fma_f32 v[112:113], v[26:27], v[110:111], v[196:197]
	v_pk_mul_f32 v[94:95], v[44:45], v[114:115] op_sel_hi:[0,1]
	v_pk_mul_f32 v[78:79], v[112:113], v[108:109]
	v_pk_mul_f32 v[86:87], v[94:95], v[110:111]
	v_lshlrev_b32_e32 v104, 16, v45
	v_and_b32_e32 v105, 0xffff0000, v45
	s_waitcnt lgkmcnt(0)
	v_add_f32_e32 v125, v124, v125
	v_add_f32_e32 v126, v125, v126
	v_add_f32_e32 v127, v126, v127
	v_add_f32_e32 v128, v127, v128
	v_add_f32_e32 v129, v128, v129
	v_add_f32_e32 v130, v129, v130
	v_add_f32_e32 v131, v130, v131
	s_and_b32 s72, s6, 3
	s_lshl_b32 s72, s72, 10
	v_add_u32_e32 v182, s72, v180
	v_add_u32_e32 v183, s72, v181
	v_mul_f32_e32 v189, 0x3fb8aa3b, v131
	ds_write_b32 v182, v189
	v_add_u32_e32 v184, 1, v146
	s_waitcnt lgkmcnt(0)
	ds_write_b32 v162, v184
	s_add_u32 s73, s6, 1
	s_mov_b32 s69, 0x100000

.Lsc_gf_go5:
	ds_read_b32 v185, v183
	ds_read_b32 v186, v183 offset:256
	ds_read_b32 v187, v183 offset:512
	s_waitcnt lgkmcnt(0)
	v_and_b32_e32 v185, v174, v185
	v_and_b32_e32 v186, v175, v186
	v_and_b32_e32 v187, v176, v187
	v_add_f32_e32 v185, v185, v186
	v_add_f32_e32 v185, v185, v187
	v_fma_f32 v124, v124, s14, v185
	v_fma_f32 v125, v125, s14, v185
	v_fma_f32 v126, v126, s14, v185
	v_fma_f32 v127, v127, s14, v185
	v_fma_f32 v128, v128, s14, v185
	v_fma_f32 v129, v129, s14, v185
	v_fma_f32 v130, v130, s14, v185
	v_fma_f32 v131, v131, s14, v185
	v_exp_f32_e64 v188, -v185
	v_exp_f32_e64 v124, -v124
	v_exp_f32_e64 v125, -v125
	v_exp_f32_e64 v126, -v126
	v_exp_f32_e64 v127, -v127
	v_exp_f32_e64 v128, -v128
	v_exp_f32_e64 v129, -v129
	v_exp_f32_e64 v130, -v130
	v_exp_f32_e64 v131, -v131
	s_nop 0
	ds_write_b32 v155, v188
	ds_write_b32 v155, v124 offset:256
	ds_write_b32 v155, v125 offset:512
	ds_write_b32 v155, v126 offset:768
	s_sleep 1
	ds_write_b32 v155, v127 offset:1024
	ds_write_b32 v155, v128 offset:1280
	ds_write_b32 v155, v129 offset:1536
	s_sleep 1
	ds_write_b32 v155, v130 offset:1792
	ds_write_b32 v155, v131 offset:2048
	v_mov_b32_e32 v161, v131
	s_waitcnt lgkmcnt(0)
	ds_read_b128 v[64:67], v153 offset:2048
	ds_read_b128 v[68:71], v153 offset:2176
	ds_read_b128 v[116:119], v153 offset:2304
	ds_read_b128 v[120:123], v153 offset:2432
	s_waitcnt lgkmcnt(0)
	v_rcp_f32_e32 v124, v116
	v_rcp_f32_e32 v125, v117
	v_rcp_f32_e32 v126, v118
	v_rcp_f32_e32 v127, v119
	v_rcp_f32_e32 v128, v120
	v_rcp_f32_e32 v129, v121
	v_rcp_f32_e32 v130, v122
	v_rcp_f32_e32 v131, v123
	s_nop 1
	v_pk_mul_f32 v[72:73], v[72:73], v[124:125]
	v_pk_mul_f32 v[80:81], v[80:81], v[124:125]
	v_pk_mul_f32 v[88:89], v[88:89], v[64:65]
	v_pk_mul_f32 v[96:97], v[96:97], v[116:117]
	v_pk_mul_f32 v[74:75], v[74:75], v[126:127]
	v_pk_mul_f32 v[82:83], v[82:83], v[126:127]
	v_pk_mul_f32 v[90:91], v[90:91], v[66:67]
	v_pk_mul_f32 v[98:99], v[98:99], v[118:119]
	v_pk_mul_f32 v[76:77], v[76:77], v[128:129]
	v_pk_mul_f32 v[84:85], v[84:85], v[128:129]
	v_pk_mul_f32 v[92:93], v[92:93], v[68:69]
	v_pk_mul_f32 v[100:101], v[100:101], v[120:121]
	v_pk_mul_f32 v[78:79], v[78:79], v[130:131]
	v_pk_mul_f32 v[86:87], v[86:87], v[130:131]
	v_pk_mul_f32 v[94:95], v[94:95], v[70:71]
	v_pk_mul_f32 v[102:103], v[102:103], v[122:123]
	s_sub_u32 s65, s6, 1
	ds_read_b128 v[148:151], v144
	s_waitcnt lgkmcnt(0)
	v_min_u32_e32 v148, v148, v149
	v_min3_u32 v148, v148, v150, v151
	s_nop 1
	v_readfirstlane_b32 s68, v148
	s_cmp_ge_u32 s68, s65
	s_cbranch_scc1 .Lsc_G_goz0
	s_mov_b32 s69, 0x100000

.Lsc_nokb5:
	ds_read_b128 v[106:109], v2 offset:0
	s_sleep 1
	ds_read_b128 v[122:125], v2 offset:16384
	s_sleep 1
	ds_read_b128 v[110:113], v3 offset:0
	s_sleep 1
	ds_read_b128 v[126:129], v3 offset:16384
	s_sleep 1
	ds_read_b128 v[114:117], v4 offset:0
	s_sleep 1
	ds_read_b128 v[130:133], v4 offset:16384
	s_sleep 1
	ds_read_b128 v[118:121], v10 offset:0
	s_sleep 1
	ds_read_b128 v[134:137], v10 offset:16384
	s_sleep 1
	s_waitcnt lgkmcnt(0)
	v_pk_add_f32 v[106:107], v[106:107], v[108:109]
	v_pk_add_f32 v[110:111], v[110:111], v[112:113]
	v_pk_add_f32 v[114:115], v[114:115], v[116:117]
	v_pk_add_f32 v[118:119], v[118:119], v[120:121]
	v_pk_add_f32 v[106:107], v[106:107], v[110:111]
	v_pk_add_f32 v[114:115], v[114:115], v[118:119]
	v_pk_add_f32 v[106:107], v[106:107], v[114:115]
	v_add_f32_e32 v64, v106, v107
	v_pk_add_f32 v[122:123], v[122:123], v[124:125]
	v_pk_add_f32 v[126:127], v[126:127], v[128:129]
	v_pk_add_f32 v[130:131], v[130:131], v[132:133]
	v_pk_add_f32 v[134:135], v[134:135], v[136:137]
	v_pk_add_f32 v[122:123], v[122:123], v[126:127]
	v_pk_add_f32 v[130:131], v[130:131], v[134:135]
	v_pk_add_f32 v[122:123], v[122:123], v[130:131]
	v_add_f32_e32 v65, v122, v123
	global_store_dword v7, v64, s[48:49]
	global_store_dword v165, v65, s[48:49]
	v_add_u32_e32 v7, s64, v7
	v_add_u32_e32 v165, s64, v165
	s_add_i32 s6, s6, 1
	v_add_u32_e32 v146, 1, v146
	s_waitcnt lgkmcnt(0)
	ds_write_b32 v145, v146
	s_waitcnt vmcnt(0)
	v_lshlrev_b32_e32 v64, 16, v54
	v_and_b32_e32 v65, 0xffff0000, v54
	v_lshlrev_b32_e32 v66, 16, v55
	v_and_b32_e32 v67, 0xffff0000, v55
	v_lshlrev_b32_e32 v68, 16, v56
	v_and_b32_e32 v69, 0xffff0000, v56
	v_lshlrev_b32_e32 v70, 16, v57
	v_and_b32_e32 v71, 0xffff0000, v57
	ds_write_b128 v153, v[64:67]
	s_sleep 1
	ds_write_b128 v153, v[68:71] offset:128
	s_waitcnt lgkmcnt(0)
	ds_read_b32 v124, v154 offset:0
	ds_read_b32 v125, v154 offset:256
	ds_read_b32 v126, v154 offset:512
	ds_read_b32 v127, v154 offset:768
	ds_read_b32 v128, v154 offset:1024
	ds_read_b32 v129, v154 offset:1280
	ds_read_b32 v130, v154 offset:1536
	ds_read_b32 v131, v154 offset:1792
	v_lshlrev_b32_e32 v108, 16, v50
	v_and_b32_e32 v109, 0xffff0000, v50
	v_lshlrev_b32_e32 v110, 16, v58
	v_and_b32_e32 v111, 0xffff0000, v58
	v_lshlrev_b32_e32 v96, 16, v46
	v_and_b32_e32 v97, 0xffff0000, v46
	v_pk_mul_f32 v[114:115], v[12:13], v[108:109]
	v_pk_fma_f32 v[112:113], v[20:21], v[110:111], v[190:191]
	v_pk_mul_f32 v[88:89], v[62:63], v[114:115] op_sel_hi:[0,1]
	v_pk_mul_f32 v[72:73], v[112:113], v[108:109]
	v_pk_mul_f32 v[80:81], v[88:89], v[110:111]
	v_lshlrev_b32_e32 v108, 16, v51
	v_and_b32_e32 v109, 0xffff0000, v51
	v_lshlrev_b32_e32 v110, 16, v59
	v_and_b32_e32 v111, 0xffff0000, v59
	v_lshlrev_b32_e32 v98, 16, v47
	v_and_b32_e32 v99, 0xffff0000, v47
	v_pk_mul_f32 v[114:115], v[14:15], v[108:109]
	v_pk_fma_f32 v[112:113], v[22:23], v[110:111], v[192:193]
	v_pk_mul_f32 v[90:91], v[62:63], v[114:115] op_sel_hi:[0,1]
	v_pk_mul_f32 v[74:75], v[112:113], v[108:109]
	v_pk_mul_f32 v[82:83], v[90:91], v[110:111]
	v_lshlrev_b32_e32 v108, 16, v52
	v_and_b32_e32 v109, 0xffff0000, v52
	v_lshlrev_b32_e32 v110, 16, v60
	v_and_b32_e32 v111, 0xffff0000, v60
	v_lshlrev_b32_e32 v100, 16, v48
	v_and_b32_e32 v101, 0xffff0000, v48
	v_pk_mul_f32 v[114:115], v[16:17], v[108:109]
	v_pk_fma_f32 v[112:113], v[24:25], v[110:111], v[194:195]
	v_pk_mul_f32 v[92:93], v[62:63], v[114:115] op_sel_hi:[0,1]
	v_pk_mul_f32 v[76:77], v[112:113], v[108:109]
	v_pk_mul_f32 v[84:85], v[92:93], v[110:111]
	v_lshlrev_b32_e32 v108, 16, v53
	v_and_b32_e32 v109, 0xffff0000, v53
	v_lshlrev_b32_e32 v110, 16, v61
	v_and_b32_e32 v111, 0xffff0000, v61
	v_lshlrev_b32_e32 v102, 16, v49
	v_and_b32_e32 v103, 0xffff0000, v49
	v_pk_mul_f32 v[114:115], v[18:19], v[108:109]
	v_pk_fma_f32 v[112:113], v[26:27], v[110:111], v[196:197]
	v_pk_mul_f32 v[94:95], v[62:63], v[114:115] op_sel_hi:[0,1]
	v_pk_mul_f32 v[78:79], v[112:113], v[108:109]
	v_pk_mul_f32 v[86:87], v[94:95], v[110:111]
	v_lshlrev_b32_e32 v104, 16, v63
	v_and_b32_e32 v105, 0xffff0000, v63
	s_waitcnt lgkmcnt(0)
	v_add_f32_e32 v125, v124, v125
	v_add_f32_e32 v126, v125, v126
	v_add_f32_e32 v127, v126, v127
	v_add_f32_e32 v128, v127, v128
	v_add_f32_e32 v129, v128, v129
	v_add_f32_e32 v130, v129, v130
	v_add_f32_e32 v131, v130, v131
	s_and_b32 s72, s6, 3
	s_lshl_b32 s72, s72, 10
	v_add_u32_e32 v182, s72, v180
	v_add_u32_e32 v183, s72, v181
	v_mul_f32_e32 v189, 0x3fb8aa3b, v131
	ds_write_b32 v182, v189
	v_add_u32_e32 v184, 1, v146
	s_waitcnt lgkmcnt(0)
	ds_write_b32 v162, v184
	s_add_u32 s73, s6, 1
	s_mov_b32 s69, 0x100000

.Lsc_nokb6:
	ds_read_b128 v[106:109], v2 offset:32768
	s_sleep 1
	ds_read_b128 v[122:125], v2 offset:49152
	s_sleep 1
	ds_read_b128 v[110:113], v3 offset:32768
	s_sleep 1
	ds_read_b128 v[126:129], v3 offset:49152
	s_sleep 1
	ds_read_b128 v[114:117], v4 offset:32768
	s_sleep 1
	ds_read_b128 v[130:133], v4 offset:49152
	s_sleep 1
	ds_read_b128 v[118:121], v10 offset:32768
	s_sleep 1
	ds_read_b128 v[134:137], v10 offset:49152
	s_sleep 1
	s_waitcnt lgkmcnt(0)
	v_pk_add_f32 v[106:107], v[106:107], v[108:109]
	v_pk_add_f32 v[110:111], v[110:111], v[112:113]
	v_pk_add_f32 v[114:115], v[114:115], v[116:117]
	v_pk_add_f32 v[118:119], v[118:119], v[120:121]
	v_pk_add_f32 v[106:107], v[106:107], v[110:111]
	v_pk_add_f32 v[114:115], v[114:115], v[118:119]
	v_pk_add_f32 v[106:107], v[106:107], v[114:115]
	v_add_f32_e32 v64, v106, v107
	v_pk_add_f32 v[122:123], v[122:123], v[124:125]
	v_pk_add_f32 v[126:127], v[126:127], v[128:129]
	v_pk_add_f32 v[130:131], v[130:131], v[132:133]
	v_pk_add_f32 v[134:135], v[134:135], v[136:137]
	v_pk_add_f32 v[122:123], v[122:123], v[126:127]
	v_pk_add_f32 v[130:131], v[130:131], v[134:135]
	v_pk_add_f32 v[122:123], v[122:123], v[130:131]
	v_add_f32_e32 v65, v122, v123
	global_store_dword v7, v64, s[48:49]
	global_store_dword v165, v65, s[48:49]
	v_add_u32_e32 v7, s64, v7
	v_add_u32_e32 v165, s64, v165
	s_add_i32 s6, s6, 1
	v_add_u32_e32 v146, 1, v146
	s_waitcnt lgkmcnt(0)
	ds_write_b32 v145, v146
	s_sub_u32 s65, s6, 1
	ds_read_b128 v[148:151], v144
	s_waitcnt lgkmcnt(0)
	v_min_u32_e32 v148, v148, v149
	v_min3_u32 v148, v148, v150, v151
	s_nop 1
	v_readfirstlane_b32 s68, v148
	s_cmp_ge_u32 s68, s65
	s_cbranch_scc1 .Lsc_G_goz2
	s_mov_b32 s69, 0x100000

.Lsc_G_goz2:
	ds_read_b128 v[106:109], v2 offset:0
	s_sleep 1
	ds_read_b128 v[122:125], v2 offset:16384
	s_sleep 1
	ds_read_b128 v[110:113], v3 offset:0
	s_sleep 1
	ds_read_b128 v[126:129], v3 offset:16384
	s_sleep 1
	ds_read_b128 v[114:117], v4 offset:0
	s_sleep 1
	ds_read_b128 v[130:133], v4 offset:16384
	s_sleep 1
	ds_read_b128 v[118:121], v10 offset:0
	s_sleep 1
	ds_read_b128 v[134:137], v10 offset:16384
	s_sleep 1
	s_waitcnt lgkmcnt(0)
	v_pk_add_f32 v[106:107], v[106:107], v[108:109]
	v_pk_add_f32 v[110:111], v[110:111], v[112:113]
	v_pk_add_f32 v[114:115], v[114:115], v[116:117]
	v_pk_add_f32 v[118:119], v[118:119], v[120:121]
	v_pk_add_f32 v[106:107], v[106:107], v[110:111]
	v_pk_add_f32 v[114:115], v[114:115], v[118:119]
	v_pk_add_f32 v[106:107], v[106:107], v[114:115]
	v_add_f32_e32 v64, v106, v107
	v_pk_add_f32 v[122:123], v[122:123], v[124:125]
	v_pk_add_f32 v[126:127], v[126:127], v[128:129]
	v_pk_add_f32 v[130:131], v[130:131], v[132:133]
	v_pk_add_f32 v[134:135], v[134:135], v[136:137]
	v_pk_add_f32 v[122:123], v[122:123], v[126:127]
	v_pk_add_f32 v[130:131], v[130:131], v[134:135]
	v_pk_add_f32 v[122:123], v[122:123], v[130:131]
	v_add_f32_e32 v65, v122, v123
	global_store_dword v7, v64, s[48:49]
	global_store_dword v165, v65, s[48:49]
	v_add_u32_e32 v7, s64, v7
	v_add_u32_e32 v165, s64, v165
	s_add_i32 s6, s6, 1
	v_add_u32_e32 v146, 1, v146
	s_waitcnt lgkmcnt(0)
	ds_write_b32 v145, v146
	s_sub_u32 s65, s6, 1
	ds_read_b128 v[148:151], v144
	s_waitcnt lgkmcnt(0)
	v_min_u32_e32 v148, v148, v149
	v_min3_u32 v148, v148, v150, v151
	s_nop 1
	v_readfirstlane_b32 s68, v148
	s_cmp_ge_u32 s68, s65
	s_cbranch_scc1 .Lsc_G_goz3
	s_mov_b32 s69, 0x100000

.Lsc_G_goz3:
	ds_read_b128 v[106:109], v2 offset:32768
	s_sleep 1
	ds_read_b128 v[122:125], v2 offset:49152
	s_sleep 1
	ds_read_b128 v[110:113], v3 offset:32768
	s_sleep 1
	ds_read_b128 v[126:129], v3 offset:49152
	s_sleep 1
	ds_read_b128 v[114:117], v4 offset:32768
	s_sleep 1
	ds_read_b128 v[130:133], v4 offset:49152
	s_sleep 1
	ds_read_b128 v[118:121], v10 offset:32768
	s_sleep 1
	ds_read_b128 v[134:137], v10 offset:49152
	s_sleep 1
	s_waitcnt lgkmcnt(0)
	v_pk_add_f32 v[106:107], v[106:107], v[108:109]
	v_pk_add_f32 v[110:111], v[110:111], v[112:113]
	v_pk_add_f32 v[114:115], v[114:115], v[116:117]
	v_pk_add_f32 v[118:119], v[118:119], v[120:121]
	v_pk_add_f32 v[106:107], v[106:107], v[110:111]
	v_pk_add_f32 v[114:115], v[114:115], v[118:119]
	v_pk_add_f32 v[106:107], v[106:107], v[114:115]
	v_add_f32_e32 v64, v106, v107
	v_pk_add_f32 v[122:123], v[122:123], v[124:125]
	v_pk_add_f32 v[126:127], v[126:127], v[128:129]
	v_pk_add_f32 v[130:131], v[130:131], v[132:133]
	v_pk_add_f32 v[134:135], v[134:135], v[136:137]
	v_pk_add_f32 v[122:123], v[122:123], v[126:127]
	v_pk_add_f32 v[130:131], v[130:131], v[134:135]
	v_pk_add_f32 v[122:123], v[122:123], v[130:131]
	v_add_f32_e32 v65, v122, v123
	global_store_dword v7, v64, s[48:49]
	global_store_dword v165, v65, s[48:49]
	v_add_u32_e32 v7, s64, v7
	v_add_u32_e32 v165, s64, v165
	s_add_i32 s6, s6, 1
	v_add_u32_e32 v146, 1, v146
	s_waitcnt lgkmcnt(0)
	ds_write_b32 v145, v146
